# v11 + attention unit prologue: per-head window length from an LDS table copy instead of a global load; unit hand-off waits vmcnt(8) instead of draining the previous unit's stores
# baseline (speedup 1.0000x reference)
; #define LAS __attribute__((address_space(3)))
; __device__ __forceinline__ void attn_phase(const Params& P, LAS unsigned char* lds, int bx, int tid_in) {
;     int tid = tid_in; asm volatile("" : "+v"(tid)); const int lane = tid & 63, wave = __builtin_amdgcn_readfirstlane(tid >> 6);
;     unsigned char* ws = P.ws;
;     bf16_t* Q = (bf16_t*)(ws + WS_Q); const bf16_t* K = (const bf16_t*)(ws + WS_K); const bf16_t* Vt = (const bf16_t*)(ws + WS_V); const bf16_t* Z = (const bf16_t*)P.out;
;     const float* tab = (const float*)(ws + WS_MISC + MISC_ATT);
;     const float lam = __builtin_bit_cast(float, __builtin_amdgcn_readfirstlane(__builtin_bit_cast(int, tab[32]))), SB = __builtin_bit_cast(float, __builtin_amdgcn_readfirstlane(__builtin_bit_cast(int, tab[33])));
;     unsigned* qctr = (unsigned*)(ws + WS_MISC + MISC_ATQ) + 64 * (bx & 7);
;     volatile LAS int* slot = (volatile LAS int*)(lds + 2 * KT_BYTES + 2 * VT_BYTES);
;     const int b = bx & 7;
;     int unext = 0; if (tid == 0) unext = (int)atomicAdd(qctr, 1u);
;     for (;;) {
;         if (tid == 0) *slot = unext;
;     ...
;         const float Df = tab[16 + h];
.LBB0_233:
	s_or_b64 exec, exec, s[6:7]
	v_mov_b32_e32 v0, v215
	v_mov_b32_e32 v1, 0x1e830000
	s_barrier
	v_and_b32_e32 v137, 63, v215
	v_lshlrev_b32_e32 v137, 4, v137
	v_cmp_gt_u32_e32 vcc, 0x200, v137
	s_and_saveexec_b64 s[10:11], vcc
	global_load_dwordx4 v[138:141], v137, s[54:55]
	v_add_u32_e32 v137, 0x11100, v137
	s_waitcnt vmcnt(0)
	ds_write_b128 v137, v[138:141]
	s_waitcnt lgkmcnt(0)
	s_or_b64 exec, exec, s[10:11]
	s_add_u32 s8, s30, 0x1e830040
	s_addc_u32 s9, s31, 0
	v_lshlrev_b32_e32 v137, 2, v215
	v_cmp_gt_u32_e32 vcc, 64, v137
	s_and_saveexec_b64 s[10:11], vcc
	global_load_dword v138, v137, s[8:9]
	v_add_u32_e32 v137, 0x11300, v137
	s_waitcnt vmcnt(0)
	ds_write_b32 v137, v138
	s_waitcnt lgkmcnt(0)
	s_or_b64 exec, exec, s[10:11]
	global_load_dwordx2 v[2:3], v1, s[30:31] offset:128
	v_lshl_add_u64 v[4:5], v[208:209], 2, s[30:31]
	s_mov_b64 s[6:7], 0x1e820000
	v_mov_b32_e32 v211, 0
	v_lshl_add_u64 v[212:213], v[4:5], 0, s[6:7]
	v_readfirstlane_b32 s10, v0
	v_cmp_eq_u32_e64 s[6:7], 0, v0
	v_mov_b32_e32 v229, 0
	s_waitcnt vmcnt(0)
	v_readfirstlane_b32 s71, v2
	v_readfirstlane_b32 s72, v3
	s_and_saveexec_b64 s[8:9], s[6:7]
	s_cbranch_execz .LBB0_235
	v_mov_b32_e32 v1, 1
	global_atomic_add v229, v[212:213], v1, off sc0
.LBB0_235:
	s_or_b64 exec, exec, s[8:9]
	s_add_u32 s73, s30, 0x1e830000
	s_addc_u32 s74, s31, 0
	s_add_u32 s38, s30, 0xe800000
	s_addc_u32 s39, s31, 0
	s_lshl_b32 s76, s20, 12
	v_ashrrev_i32_e32 v3, 4, v0
	v_lshlrev_b32_e32 v6, 4, v0
	v_add_u32_e32 v5, s76, v3
	v_and_b32_e32 v4, 0xf0, v6
	s_movk_i32 s18, 0x110
	v_mad_u64_u32 v[216:217], s[8:9], v3, s18, v[4:5]
	v_ashrrev_i32_e32 v7, 3, v0
	v_and_b32_e32 v218, 0x70, v6
	s_movk_i32 s8, 0x88
	v_mad_u64_u32 v[220:221], s[8:9], v7, s8, v[218:219]
	v_and_b32_e32 v214, 31, v0
	v_add_u32_e32 v221, 64, v169
	v_bfe_u32 v1, v0, 5, 1
	v_lshl_or_b32 v232, v5, 12, v4
	v_mad_u32_u24 v5, v214, s18, 0
	v_cmp_lt_i32_e32 vcc, v171, v221
	s_ashr_i32 s10, s10, 1
	v_lshlrev_b32_e32 v2, 3, v1
	v_lshl_add_u32 v235, v1, 4, v5
	v_lshlrev_b32_e32 v237, 2, v1
	v_cndmask_b32_e32 v1, v219, v171, vcc
	s_movk_i32 s11, 0xffe0
	v_lshlrev_b32_e32 v217, 2, v1
	v_mov_b32_e32 v1, s10
	v_bfi_b32 v238, s11, v1, v0
	v_and_b32_e32 v230, 63, v0
	v_sub_u32_e32 v0, v238, v237
	s_lshl_b32 s8, s20, 24
	v_subrev_u32_e32 v239, 32, v0
	v_lshl_add_u32 v0, v7, 13, s8
	v_or_b32_e32 v0, v0, v218
	v_add_u32_e32 v240, 0xf00080, v0
	v_lshl_add_u32 v0, v3, 12, s8
	v_lshl_add_u32 v231, s20, 11, v7
	v_mul_i32_i24_e32 v6, 0xffffff78, v214
	v_or_b32_e32 v0, v0, v4
	s_add_i32 s77, 0, 0x11000
	s_mov_b32 s20, 2.0
	s_mov_b32 s22, 0x41000000
	s_mov_b32 s40, 0x41200000
	s_mov_b32 s42, 0x41800000
	s_mov_b32 s52, 0x41900000
	s_mov_b32 s58, 0x41c00000
	s_mov_b32 s60, 0x41d00000
	s_and_b32 s75, s10, 0xffffffe0
	s_mov_b32 s19, 0
	v_add_u32_e32 v233, 0, v216
	v_add_u32_e32 v234, 0, v220
	v_add3_u32 v236, v5, v6, v2
	v_add_u32_e32 v241, 0x40f00, v0
	v_mov_b32_e32 v242, s77
	v_mov_b32_e32 v243, 1
	s_mov_b32 s78, 0x45800000
	v_lshlrev_b32_e32 v222, 1, v2
	s_mov_b32 s79, 0x20000
	s_mov_b32 s80, 0x80000
	s_mov_b32 s21, 0x40400000
	s_mov_b32 s23, 0x41100000
	s_mov_b32 s41, 0x41300000
	s_mov_b32 s43, 0x41880000
	s_mov_b32 s53, 0x41980000
	s_mov_b32 s59, 0x41c80000
	s_mov_b32 s61, 0x41d80000
	v_mov_b32_e32 v244, 0xff800000
	v_mov_b32_e32 v245, 0x358637bd
	s_mov_b32 s81, 0x800000
	s_waitcnt vmcnt(0)
	s_branch .LBB0_238

; __device__ __forceinline__ void attn_phase(const Params& P, LAS unsigned char* lds, int bx, int tid_in) {
;     ...
;     for (;;) {
;         if (tid == 0) *slot = unext;
;         __syncthreads();
;         const int u = __builtin_amdgcn_readfirstlane(*slot);
.LBB0_238:
	s_and_saveexec_b64 s[8:9], s[6:7]
	s_cbranch_execz .LBB0_240
	v_mov_b32_e32 v0, s77
	s_waitcnt vmcnt(8)
	ds_write_b32 v0, v229

; #define AT_LOADK(tt) do { const unsigned ko = kgo + (unsigned)(tt) * (64 * BR * 2); ks0 = *(const u32x4*)((const char*)K + ko); ks1 = *(const u32x4*)((const char*)K + ko + 32 * BR * 2); } while (0)
; __device__ __forceinline__ void attn_unit(int b, int h, int qb, bf16_t* Q, const bf16_t* __restrict__ K, const bf16_t* __restrict__ Vt, const bf16_t* __restrict__ Z, const float* __restrict__ hg, float lam, ...
;     const int r32 = lane & 31, hi = lane >> 5;
;     const int q0u = qb * 256, qw0 = q0u + 32 * wave;
;     const size_t rowbase = (size_t)b * SEQ;
;     const float slope2 = __builtin_bit_cast(float, __builtin_amdgcn_readfirstlane(__builtin_bit_cast(int, tab[h])));
;     bf16x8 qf[2][4];
;     { const bf16_t* qp = Q + (rowbase + qw0 + r32) * BR + h * 128 + 8 * hi;
; #pragma unroll
;       for (int sub = 0; sub < 2; ++sub)
; #pragma unroll
;           for (int d0 = 0; d0 < 4; ++d0) qf[sub][d0] = *(const bf16x8*)(qp + sub * 64 + d0 * 16); }
;     const unsigned kgo = (unsigned)(((rowbase + (tid >> 4)) * BR + h * 128 + (tid & 15) * 8) * 2);
;     const int kl = (tid >> 4) * KROW + (tid & 15) * 16;
;     const unsigned vgo = (unsigned)((((size_t)b * BR + h * 128 + (tid >> 3)) * SEQ + (tid & 7) * 8) * 2);
;     const int vl = AT_VOFF + (tid >> 3) * VROW + (tid & 7) * 16;
;     const int NT = 4 * (qb + 1), last_w = (qw0 + 31) >> 6;
;     int tlo_w = 0; if (Dwin < 4096.f) { const int kmin_w = qw0 - (int)Dwin - 1; tlo_w = kmin_w > 0 ? (kmin_w >> 6) : 0; }
;     f32x16 o[2][4];
; #pragma unroll
;     for (int s = 0; s < 2; ++s)
; #pragma unroll
;         for (int d = 0; d < 4; ++d)
; #pragma unroll
;             for (int r = 0; r < 16; ++r) o[s][d][r] = 0.f;
;     float lsum[2] = {0.f, 0.f};
;     u32x4 ks0, ks1, vs0, vs1;
;     ...
;     AT_LOADK(tfirst); AT_LOADV(tfirst); AT_WRITEK(tfirst & 1); AT_WRITEV(tfirst & 1);
;     __syncthreads();
; __device__ __forceinline__ void attn_phase(const Params& P, LAS unsigned char* lds, int bx, int tid_in) {
;     ...
;         const int h = 15 - (u >> 4), qb = 15 - (u & 15);
;         const float Df = tab[16 + h];
;         int tfirst = 0;
;         if (Df < 4096.f) { const int kmin = qb * 256 - (int)Df - 1; tfirst = kmin > 0 ? (kmin >> 6) : 0; }
;         tfirst = __builtin_amdgcn_readfirstlane(tfirst);
.LBB0_243:
	s_or_b64 exec, exec, s[8:9]
	s_ashr_i32 s10, s11, 4
	s_sub_i32 s18, 31, s10
	s_sub_i32 s8, 15, s10
	s_andn2_b32 s11, 15, s11
	s_lshl_b32 s62, s18, 2
	s_add_i32 s62, s62, 0x112c0
	v_mov_b32_e32 v0, s62
	ds_read_b32 v0, v0
	s_lshl_b32 s62, s11, 8
	s_mov_b32 s9, s19
	v_mov_b32_e32 v223, v211
	v_mov_b32_e32 v225, 0
	v_mov_b32_e32 v224, v225
	v_mov_b32_e32 v79, v225
	v_mov_b32_e32 v78, v225
	v_mov_b32_e32 v77, v225
	v_mov_b32_e32 v76, v225
	v_mov_b32_e32 v75, v225
	v_mov_b32_e32 v74, v225
	v_mov_b32_e32 v73, v225
	v_mov_b32_e32 v72, v225
	v_mov_b32_e32 v71, v225
	v_mov_b32_e32 v70, v225
	v_mov_b32_e32 v69, v225
	v_mov_b32_e32 v68, v225
	v_mov_b32_e32 v67, v225
	v_mov_b32_e32 v66, v225
	v_mov_b32_e32 v65, v225
	v_mov_b32_e32 v64, v225
	v_mov_b32_e32 v63, v225
	v_mov_b32_e32 v62, v225
	v_mov_b32_e32 v61, v225
	v_mov_b32_e32 v60, v225
	v_mov_b32_e32 v59, v225
	v_mov_b32_e32 v58, v225
	v_mov_b32_e32 v57, v225
	v_mov_b32_e32 v56, v225
	v_mov_b32_e32 v55, v225
	v_mov_b32_e32 v54, v225
	v_mov_b32_e32 v53, v225
	v_mov_b32_e32 v52, v225
	v_mov_b32_e32 v51, v225
	v_mov_b32_e32 v50, v225
	v_mov_b32_e32 v49, v225
	v_mov_b32_e32 v48, v225
	v_mov_b32_e32 v31, v225
	v_mov_b32_e32 v30, v225
	v_mov_b32_e32 v29, v225
	v_mov_b32_e32 v28, v225
	v_mov_b32_e32 v27, v225
	v_mov_b32_e32 v26, v225
	v_mov_b32_e32 v25, v225
	v_mov_b32_e32 v24, v225
	v_mov_b32_e32 v23, v225
	v_mov_b32_e32 v22, v225
	v_mov_b32_e32 v21, v225
	v_mov_b32_e32 v20, v225
	v_mov_b32_e32 v19, v225
	v_mov_b32_e32 v18, v225
	v_mov_b32_e32 v17, v225
	v_mov_b32_e32 v16, v225
	v_mov_b32_e32 v15, v225
	v_mov_b32_e32 v14, v225
	v_mov_b32_e32 v13, v225
	v_mov_b32_e32 v12, v225
	v_mov_b32_e32 v11, v225
	v_mov_b32_e32 v10, v225
	v_mov_b32_e32 v9, v225
	v_mov_b32_e32 v8, v225
	v_mov_b32_e32 v7, v225
	v_mov_b32_e32 v6, v225
	v_mov_b32_e32 v5, v225
	v_mov_b32_e32 v4, v225
	v_mov_b32_e32 v127, v225
	v_mov_b32_e32 v126, v225
	v_mov_b32_e32 v125, v225
	v_mov_b32_e32 v124, v225
	v_mov_b32_e32 v123, v225
	v_mov_b32_e32 v122, v225
	v_mov_b32_e32 v121, v225
	v_mov_b32_e32 v120, v225
	v_mov_b32_e32 v119, v225
	v_mov_b32_e32 v118, v225
	v_mov_b32_e32 v117, v225
	v_mov_b32_e32 v116, v225
	v_mov_b32_e32 v115, v225
	v_mov_b32_e32 v114, v225
	s_waitcnt lgkmcnt(0)
	v_cvt_i32_f32_e32 v1, v0
	v_cmp_gt_f32_e32 vcc, s78, v0
	v_mov_b32_e32 v113, v225
	v_mov_b32_e32 v112, v225
	v_readfirstlane_b32 s18, v1
	s_not_b32 s63, s18
	s_add_i32 s18, s62, s63
	s_max_i32 s18, s18, 0
	s_lshr_b32 s18, s18, 6
	s_and_b64 s[64:65], vcc, exec
	s_cselect_b32 s64, s18, 0
	s_add_i32 s84, s62, s75
	s_lshl_b64 s[66:67], s[8:9], 2
	s_add_u32 s86, s73, s66
	s_addc_u32 s87, s74, s67
	s_ashr_i32 s9, s84, 31
	s_add_u32 s82, s84, s76
	s_addc_u32 s83, s9, 0
	s_lshl_b32 s18, s8, 7
	s_lshl_b32 s8, s8, 8
	s_lshl_b32 s65, s64, 18
	s_add_i32 s8, s65, s8
	v_add_u32_e32 v0, s18, v231
	v_add_u32_e32 v210, s8, v232
	s_lshl_b32 s66, s64, 7
	v_lshl_or_b32 v2, v0, 13, v218
	v_lshl_add_u64 v[0:1], s[38:39], 0, v[210:211]
	v_or_b32_e32 v32, s82, v214
	v_mov_b32_e32 v33, s83
	global_load_dwordx4 v[160:163], v210, s[38:39]
	v_add_u32_e32 v210, s66, v2
	v_add_co_u32_e64 v0, s[8:9], s79, v0
	v_lshlrev_b64 v[32:33], 12, v[32:33]
	s_nop 0
	v_addc_co_u32_e64 v1, s[8:9], 0, v1, s[8:9]
	v_lshl_add_u64 v[2:3], s[36:37], 0, v[210:211]
	v_lshl_add_u64 v[32:33], s[34:35], 0, v[32:33]
	global_load_dword v34, v211, s[86:87]
	global_load_dwordx4 v[164:167], v210, s[36:37]
	global_load_dwordx4 v[168:171], v[0:1], off
	v_add_co_u32_e64 v0, s[8:9], s80, v2
	v_lshl_add_u64 v[32:33], s[18:19], 1, v[32:33]
	s_nop 0
	v_addc_co_u32_e64 v1, s[8:9], 0, v3, s[8:9]
	v_lshl_add_u64 v[32:33], v[32:33], 0, v[222:223]
	global_load_dwordx4 v[172:175], v[0:1], off
	global_load_dwordx4 v[176:179], v[32:33], off
	global_load_dwordx4 v[180:183], v[32:33], off offset:32
	global_load_dwordx4 v[184:187], v[32:33], off offset:64
	global_load_dwordx4 v[188:191], v[32:33], off offset:96
	global_load_dwordx4 v[192:195], v[32:33], off offset:128
	global_load_dwordx4 v[196:199], v[32:33], off offset:160
	global_load_dwordx4 v[200:203], v[32:33], off offset:192
	global_load_dwordx4 v[204:207], v[32:33], off offset:224
	s_lshl_b32 s85, s11, 2
	s_add_i32 s85, s85, 4
	s_bitcmp1_b32 s64, 0
	s_cselect_b32 s8, 0x4400, 0
	s_add_i32 s8, s8, 0
	v_add_u32_e32 v33, s8, v220
	v_add_u32_e32 v32, s8, v216
	v_add_u32_e32 v35, 0x8800, v33
	v_add_u32_e32 v33, 0xaa00, v33
	v_mov_b32_e32 v3, v225
	v_mov_b32_e32 v2, v225
	v_mov_b32_e32 v1, v225
	v_mov_b32_e32 v0, v225
	v_mov_b32_e32 v111, v225
	v_mov_b32_e32 v110, v225
	v_mov_b32_e32 v109, v225
	v_mov_b32_e32 v108, v225
	v_mov_b32_e32 v107, v225
	v_mov_b32_e32 v106, v225
	v_mov_b32_e32 v105, v225
	v_mov_b32_e32 v104, v225
	v_mov_b32_e32 v103, v225
	v_mov_b32_e32 v102, v225
	v_mov_b32_e32 v101, v225
	v_mov_b32_e32 v100, v225
	v_mov_b32_e32 v99, v225
	v_mov_b32_e32 v98, v225
	v_mov_b32_e32 v97, v225
	v_mov_b32_e32 v96, v225
	v_mov_b32_e32 v95, v225
	v_mov_b32_e32 v94, v225
	v_mov_b32_e32 v93, v225
	v_mov_b32_e32 v92, v225
	v_mov_b32_e32 v91, v225
	s_cmp_ge_i32 s64, s85
	v_mov_b32_e32 v90, v225
	v_mov_b32_e32 v89, v225
	v_mov_b32_e32 v88, v225
	v_mov_b32_e32 v87, v225
	v_mov_b32_e32 v86, v225
	v_mov_b32_e32 v85, v225
	v_mov_b32_e32 v84, v225
	v_mov_b32_e32 v83, v225
	v_mov_b32_e32 v82, v225
	v_mov_b32_e32 v81, v225
	v_mov_b32_e32 v80, v225
	v_mov_b32_e32 v47, v225
	v_mov_b32_e32 v46, v225
	v_mov_b32_e32 v45, v225
	v_mov_b32_e32 v44, v225
	s_waitcnt vmcnt(12)
	ds_write_b128 v32, v[160:163]
	s_waitcnt vmcnt(9)
	ds_write_b128 v32, v[168:171] offset:8704
	ds_write2_b64 v35, v[164:165], v[166:167] offset1:1
	s_waitcnt vmcnt(8)
	ds_write2_b64 v33, v[172:173], v[174:175] offset1:1
	v_readfirstlane_b32 s86, v34
	v_mov_b32_e32 v43, v225
	v_mov_b32_e32 v42, v225
	v_mov_b32_e32 v41, v225
	v_mov_b32_e32 v40, v225
	v_mov_b32_e32 v39, v225
	v_mov_b32_e32 v38, v225
	v_mov_b32_e32 v37, v225
	v_mov_b32_e32 v36, v225
	v_mov_b32_e32 v35, v225
	v_mov_b32_e32 v34, v225
	v_mov_b32_e32 v33, v225
	v_mov_b32_e32 v32, v225
	s_waitcnt lgkmcnt(0)
	s_barrier
; #define LAS __attribute__((address_space(3)))
; #define AT_LOADK(tt) do { const unsigned ko = kgo + (unsigned)(tt) * (64 * BR * 2); ks0 = *(const u32x4*)((const char*)K + ko); ks1 = *(const u32x4*)((const char*)K + ko + 32 * BR * 2); } while (0)
; #define AT_LOADV(tt) do { const unsigned vo = vgo + (unsigned)(tt) * 128; vs0 = *(const u32x4*)((const char*)Vt + vo); vs1 = *(const u32x4*)((const char*)Vt + vo + 64 * SEQ * 2); } while (0)
; #define AT_WRITEK(buf) do { *(LAS u32x4*)(lds + (buf) * KT_BYTES + kl) = ks0; *(LAS u32x4*)(lds + (buf) * KT_BYTES + kl + 32 * KROW) = ks1; } while (0)
; #define AT_WRITEV(buf) do { \
;         *(LAS u32x2*)(lds + (buf) * VT_BYTES + vl) = (u32x2){vs0.x, vs0.y}; *(LAS u32x2*)(lds + (buf) * VT_BYTES + vl + 8) = (u32x2){vs0.z, vs0.w}; \
;         *(LAS u32x2*)(lds + (buf) * VT_BYTES + vl + 64 * VROW) = (u32x2){vs1.x, vs1.y}; *(LAS u32x2*)(lds + (buf) * VT_BYTES + vl + 64 * VROW + 8) = (u32x2){vs1.z, vs1.w}; } while (0)
; __device__ __forceinline__ void attn_unit(int b, int h, int qb, bf16_t* Q, const bf16_t* __restrict__ K, const bf16_t* __restrict__ Vt, const bf16_t* __restrict__ Z, const float* __restrict__ hg, float lam, ...
;     ...
;     const int NT = 4 * (qb + 1), last_w = (qw0 + 31) >> 6;
;     int tlo_w = 0; if (Dwin < 4096.f) { const int kmin_w = qw0 - (int)Dwin - 1; tlo_w = kmin_w > 0 ? (kmin_w >> 6) : 0; }
;     f32x16 o[2][4];
; #pragma unroll
;     for (int s = 0; s < 2; ++s)
; #pragma unroll
;         for (int d = 0; d < 4; ++d)
; #pragma unroll
;             for (int r = 0; r < 16; ++r) o[s][d][r] = 0.f;
;     float lsum[2] = {0.f, 0.f};
;     u32x4 ks0, ks1, vs0, vs1;
;     ...
;     AT_LOADK(tfirst); AT_LOADV(tfirst); AT_WRITEK(tfirst & 1); AT_WRITEV(tfirst & 1);
;     __syncthreads();
;     for (int t = tfirst; t < NT; ++t) {
;         const int cur = t & 1; const bool more = (t + 1 < NT), active = (t <= last_w) && (t >= tlo_w), band = (64 * t + 63 > qw0);
;         const LAS unsigned char* kb = lds + cur * KT_BYTES + r32 * KROW + hi * 16;
;         const LAS unsigned char* vb = lds + AT_VOFF + cur * VT_BYTES + r32 * VROW + hi * 8;
;         if (more) AT_LOADK(t + 1);
	s_cbranch_scc1 .LBB0_236
	s_add_i32 s8, s84, s63
	s_max_i32 s8, s8, 0
	s_ashr_i32 s87, s84, 6
	s_lshr_b32 s11, s8, 6
	s_and_b64 s[8:9], vcc, exec
	s_cselect_b32 s88, s11, 0
	v_add_u32_e32 v0, s62, v239
	s_lshl_b32 s89, s64, 6
	v_subrev_u32_e32 v223, s89, v0
	v_add_u32_e32 v0, s62, v238
	v_sub_u32_e32 v246, v237, v0
	v_add_u32_e32 v0, s66, v240
	s_lshl_b32 s8, s10, 20
	v_subrev_u32_e32 v226, s8, v0
	v_add_u32_e32 v0, s65, v241
	s_lshl_b32 s8, s10, 8
	v_mov_b32_e32 v32, v211
	v_mov_b32_e32 v33, v211
	v_mov_b32_e32 v46, v211
	v_mov_b32_e32 v47, v211
	v_subrev_u32_e32 v210, s8, v0
	v_mov_b32_e32 v34, v211
	v_mov_b32_e32 v35, v211
	v_mov_b32_e32 v36, v211
	v_mov_b32_e32 v37, v211
	v_mov_b32_e32 v38, v211
	v_mov_b32_e32 v39, v211
	v_mov_b32_e32 v40, v211
	v_mov_b32_e32 v41, v211
	v_mov_b32_e32 v42, v211
	v_mov_b32_e32 v43, v211
	v_mov_b32_e32 v44, v211
	v_mov_b32_e32 v45, v211
	v_mov_b32_e32 v224, 0
	v_mov_b64_e32 v[94:95], v[46:47]
	v_mov_b64_e32 v[110:111], v[46:47]
	v_mov_b64_e32 v[126:127], v[46:47]
	v_mov_b64_e32 v[0:1], v[32:33]
	v_mov_b64_e32 v[16:17], v[32:33]
	v_mov_b64_e32 v[62:63], v[46:47]
	v_mov_b64_e32 v[78:79], v[46:47]
	v_mov_b64_e32 v[92:93], v[44:45]
	v_mov_b64_e32 v[90:91], v[42:43]
	v_mov_b64_e32 v[88:89], v[40:41]
	v_mov_b64_e32 v[86:87], v[38:39]
	v_mov_b64_e32 v[84:85], v[36:37]
	v_mov_b64_e32 v[82:83], v[34:35]
	v_mov_b64_e32 v[80:81], v[32:33]
	v_mov_b64_e32 v[108:109], v[44:45]
	v_mov_b64_e32 v[106:107], v[42:43]
	v_mov_b64_e32 v[104:105], v[40:41]
	v_mov_b64_e32 v[102:103], v[38:39]
	v_mov_b64_e32 v[100:101], v[36:37]
	v_mov_b64_e32 v[98:99], v[34:35]
	v_mov_b64_e32 v[96:97], v[32:33]
	v_mov_b64_e32 v[124:125], v[44:45]
	v_mov_b64_e32 v[122:123], v[42:43]
	v_mov_b64_e32 v[120:121], v[40:41]
	v_mov_b64_e32 v[118:119], v[38:39]
	v_mov_b64_e32 v[116:117], v[36:37]
	v_mov_b64_e32 v[114:115], v[34:35]
	v_mov_b64_e32 v[112:113], v[32:33]
	v_mov_b64_e32 v[2:3], v[34:35]
	v_mov_b64_e32 v[4:5], v[36:37]
	v_mov_b64_e32 v[6:7], v[38:39]
	v_mov_b64_e32 v[8:9], v[40:41]
	v_mov_b64_e32 v[10:11], v[42:43]
	v_mov_b64_e32 v[12:13], v[44:45]
	v_mov_b64_e32 v[14:15], v[46:47]
	v_mov_b64_e32 v[18:19], v[34:35]
	v_mov_b64_e32 v[20:21], v[36:37]
	v_mov_b64_e32 v[22:23], v[38:39]
	v_mov_b64_e32 v[24:25], v[40:41]
	v_mov_b64_e32 v[26:27], v[42:43]
	v_mov_b64_e32 v[28:29], v[44:45]
	v_mov_b64_e32 v[30:31], v[46:47]
	v_mov_b64_e32 v[60:61], v[44:45]
	v_mov_b64_e32 v[58:59], v[42:43]
	v_mov_b64_e32 v[56:57], v[40:41]
	v_mov_b64_e32 v[54:55], v[38:39]
	v_mov_b64_e32 v[52:53], v[36:37]
	v_mov_b64_e32 v[50:51], v[34:35]
	v_mov_b64_e32 v[48:49], v[32:33]
	v_mov_b64_e32 v[76:77], v[44:45]
	v_mov_b64_e32 v[74:75], v[42:43]
	v_mov_b64_e32 v[72:73], v[40:41]
	v_mov_b64_e32 v[70:71], v[38:39]
	v_mov_b64_e32 v[68:69], v[36:37]
	v_mov_b64_e32 v[66:67], v[34:35]
	v_mov_b64_e32 v[64:65], v[32:33]
	v_mov_b32_e32 v225, v224
	global_load_dwordx4 v[160:163], v210, s[38:39]
	v_add_u32_e32 v128, 0x20000, v210
	global_load_dwordx4 v[168:171], v128, s[38:39]
	global_load_dwordx4 v[164:167], v226, s[36:37]
	v_add_u32_e32 v128, 0x80000, v226
	global_load_dwordx4 v[172:175], v128, s[36:37]
